# previous plus one static s_setprio 1 for waves 4-7 during the FoX attention phase (restored to 0 after)
# baseline (speedup 1.0000x reference)
; __global__ void __launch_bounds__(MEGA_THREADS, 2) mega(MArgs a) {
;     ...
;                 if (EN_FOX && (sub & SUB_FOX)) {
;                     float gqm = fabsf(in[6][l * 64 + lane]), gkm = fabsf(in[7][l * 64 + lane]);
; #pragma unroll
;                     for (int o = 1; o < 64; o <<= 1) { gqm = fmaxf(gqm, __shfl_xor(gqm, o)); gkm = fmaxf(gkm, __shfl_xor(gkm, o)); }
;                     const float thr = -(152.f + 2.f * C2 * 64.f * gqm * gkm);
.LBB9_233:
	s_and_b64 vcc, exec, s[6:7]
	s_cbranch_vccz .LBB9_349
	s_add_u32 s2, s76, 0x1e100000
	s_addc_u32 s3, s77, 0
	v_writelane_b32 v255, s2, 1
	s_add_u32 s44, s76, 0x1e300000
	s_addc_u32 s45, s77, 0
	v_writelane_b32 v255, s3, 2
	v_readlane_b32 s2, v254, 0
	v_readlane_b32 s3, v254, 1
	s_load_dword s2, s[2:3], 0xe8
	v_writelane_b32 v255, s67, 3
	s_mov_b64 s[6:7], -1
	s_waitcnt lgkmcnt(0)
	s_add_i32 s71, s2, s82
	s_cmp_gt_i32 s67, 1
	s_cbranch_scc0 .LBB9_626
	s_add_u32 s46, s76, 0x1c100000
	s_addc_u32 s47, s77, 0
	s_add_u32 s28, s76, 0x4100000
	s_addc_u32 s29, s77, 0
	s_add_u32 s2, s76, 0x8100000
	s_addc_u32 s3, s77, 0
	s_add_u32 s25, s76, 0x1e200000
	s_addc_u32 s24, s77, 0
	s_add_u32 s60, s76, 0x1e400000
	v_writelane_b32 v255, s2, 4
	s_addc_u32 s61, s77, 0
	s_nop 0
	v_writelane_b32 v255, s3, 5
	s_add_u32 s2, s76, 0x20100000
	s_addc_u32 s3, s77, 0
	v_writelane_b32 v255, s2, 6
	s_nop 1
	v_writelane_b32 v255, s3, 7
	s_add_u32 s2, s76, 0x20200000
	s_addc_u32 s3, s77, 0
	v_writelane_b32 v255, s2, 8
	s_nop 1
	v_writelane_b32 v255, s3, 9
	s_nop 0
	v_readlane_b32 s2, v255, 3
	s_cmp_gt_i32 s2, 2
	v_writelane_b32 v255, s24, 10
	s_cbranch_scc0 .LBB9_454
	s_bitcmp0_b32 s71, 7
	s_cbranch_scc1 .LBB9_350
	v_readfirstlane_b32 s100, v212
	s_lshr_b32 s100, s100, 6
	s_cmp_lt_u32 s100, 4
	s_cbranch_scc1 .Lfox_prio_done
	s_setprio 1
.Lfox_prio_done:
	s_load_dwordx4 s[4:7], s[84:85], 0x30
	v_readlane_b32 s2, v254, 51
	s_waitcnt vmcnt(0)
	v_xor_b32_e32 v6, 1, v244
	s_add_u32 s79, s76, 0x6100000
	v_lshl_or_b32 v0, s2, 6, v248
	v_lshlrev_b64 v[2:3], 2, v[0:1]
	s_waitcnt lgkmcnt(0)
	v_lshl_add_u64 v[4:5], s[4:5], 0, v[2:3]
	v_lshl_add_u64 v[2:3], s[6:7], 0, v[2:3]
	global_load_dword v2, v[2:3], off
	s_addc_u32 s81, s77, 0
	global_load_dword v0, v[4:5], off
	v_and_b32_e32 v5, 64, v244
	v_add_u32_e32 v5, 64, v5
	v_cmp_lt_i32_e32 vcc, v6, v5
	v_readlane_b32 s3, v254, 52
	s_lshl_b32 s52, s2, 9
	v_cndmask_b32_e32 v6, v244, v6, vcc
	v_lshlrev_b32_e32 v6, 2, v6
	s_lshl_b64 s[2:3], s[52:53], 2
	s_add_u32 s2, s76, s2
	s_addc_u32 s3, s77, s3
	s_add_u32 s18, s2, 0x8000
	s_addc_u32 s19, s3, 0
	v_readlane_b32 s2, v254, 11
	s_add_u32 s2, s2, s82
	s_waitcnt vmcnt(0)
	v_and_b32_e32 v3, 0x7fffffff, v2
	ds_bpermute_b32 v3, v6, v3
	v_and_b32_e32 v4, 0x7fffffff, v0
	ds_bpermute_b32 v4, v6, v4
	v_max_f32_e64 v2, |v2|, |v2|
	v_max_f32_e64 v0, |v0|, |v0|
	s_waitcnt lgkmcnt(1)
	v_max_f32_e32 v3, v3, v3
	v_max_f32_e32 v2, v2, v3
	v_xor_b32_e32 v3, 2, v244
	v_cmp_lt_i32_e32 vcc, v3, v5
	s_waitcnt lgkmcnt(0)
	v_max_f32_e32 v4, v4, v4
	v_max_f32_e32 v0, v0, v4
	v_cndmask_b32_e32 v3, v244, v3, vcc
	v_lshlrev_b32_e32 v3, 2, v3
	ds_bpermute_b32 v4, v3, v0
	ds_bpermute_b32 v3, v3, v2
	v_writelane_b32 v255, s2, 11
	v_readlane_b32 s2, v254, 12
	s_addc_u32 s3, s2, s83
	s_waitcnt lgkmcnt(1)
	v_max_f32_e32 v4, v4, v4
	s_waitcnt lgkmcnt(0)
	v_max_f32_e32 v3, v3, v3
	v_max_f32_e32 v2, v2, v3
	v_xor_b32_e32 v3, 4, v244
	v_cmp_lt_i32_e32 vcc, v3, v5
	v_max_f32_e32 v0, v0, v4
	s_nop 0
	v_cndmask_b32_e32 v3, v244, v3, vcc
	v_lshlrev_b32_e32 v3, 2, v3
	ds_bpermute_b32 v4, v3, v0
	ds_bpermute_b32 v3, v3, v2
	s_waitcnt lgkmcnt(1)
	v_max_f32_e32 v4, v4, v4
	s_waitcnt lgkmcnt(0)
	v_max_f32_e32 v3, v3, v3
	v_max_f32_e32 v2, v2, v3
	v_xor_b32_e32 v3, 8, v244
	v_cmp_lt_i32_e32 vcc, v3, v5
	v_max_f32_e32 v0, v0, v4
	s_nop 0
	v_cndmask_b32_e32 v3, v244, v3, vcc
	v_lshlrev_b32_e32 v3, 2, v3
	ds_bpermute_b32 v4, v3, v0
	ds_bpermute_b32 v3, v3, v2
	s_waitcnt lgkmcnt(1)
	v_max_f32_e32 v4, v4, v4
	s_waitcnt lgkmcnt(0)
	v_max_f32_e32 v3, v3, v3
	v_max_f32_e32 v2, v2, v3
	v_xor_b32_e32 v3, 16, v244
	v_cmp_lt_i32_e32 vcc, v3, v5
	v_max_f32_e32 v0, v0, v4
	s_nop 0
	v_cndmask_b32_e32 v3, v244, v3, vcc
	v_lshlrev_b32_e32 v3, 2, v3
	ds_bpermute_b32 v4, v3, v0
	ds_bpermute_b32 v3, v3, v2
	s_waitcnt lgkmcnt(1)
	v_max_f32_e32 v4, v4, v4
	s_waitcnt lgkmcnt(0)
	v_max_f32_e32 v3, v3, v3
	v_max_f32_e32 v2, v2, v3
	v_xor_b32_e32 v3, 32, v244
	v_cmp_lt_i32_e32 vcc, v3, v5
	v_max_f32_e32 v0, v0, v4
	s_nop 0
	v_cndmask_b32_e32 v3, v244, v3, vcc
	v_lshlrev_b32_e32 v3, 2, v3
	ds_bpermute_b32 v4, v3, v0
	ds_bpermute_b32 v3, v3, v2
	s_waitcnt lgkmcnt(1)
	v_max_f32_e32 v4, v4, v4
	v_max_f32_e32 v0, v0, v4
	s_waitcnt lgkmcnt(0)
	v_max_f32_e32 v3, v3, v3
	v_max_f32_e32 v2, v2, v3
	v_mul_f32_e32 v0, 0x41b8aa3b, v0
	v_fmaak_f32 v227, v2, v0, 0x42840000
	s_branch .LBB9_239

; #define LAS __attribute__((address_space(3)))
; template <bool FINAL> __device__ __forceinline__ void lru_pass(int l, int bx, int G, const float* const* in, const bf16_t* LX, const bf16_t* LG, bf16_t* YL, float* APROD, float* HEND, LAS unsigned char* lds, int tid) {
;     const int n = bx & 15, e = tid & 63, ch = n * 64 + e;
;     { const float* wa = in[10] + (size_t)l * 65536 + (size_t)n * 4096; const float* wx = in[12] + (size_t)l * 65536 + (size_t)n * 4096;
;         float wv_[16];
; #pragma unroll
;         for (int k = 0; k < 16; ++k) { const int i = tid + MEGA_THREADS * k; wv_[k] = (i >> 12) ? wx[i & 4095] : wa[i & 4095]; }
; __global__ void __launch_bounds__(MEGA_THREADS, 2) mega(MArgs a) {
;     ...
;                 __syncthreads();
;                 if (EN_LRU && (sub & SUB_LRU)) lru_pass<true>(l, bx, G, in, LX, LG, YL, APROD, HEND, lds, tid);
.LBB9_350:
	s_setprio 0
	s_bitcmp0_b32 s71, 4
	s_movk_i32 s81, 0x2000
	s_movk_i32 s79, 0x4000
	s_waitcnt vmcnt(0)
	s_barrier
	s_cbranch_scc1 .LBB9_427
	v_readlane_b32 s22, v254, 51
	s_load_dwordx8 s[8:15], s[84:85], 0x40
	s_load_dwordx4 s[16:19], s[84:85], 0x60
	s_load_dwordx2 s[6:7], s[84:85], 0x70
	v_readlane_b32 s23, v254, 52
	s_mov_b32 s23, s53
	s_and_b32 s2, s90, 15
	s_lshl_b64 s[4:5], s[22:23], 18
	s_waitcnt lgkmcnt(0)
	s_add_u32 s3, s12, s4
	s_addc_u32 s13, s13, s5
	s_lshl_b32 s20, s2, 14
	s_add_u32 s12, s3, s20
	s_addc_u32 s13, s13, 0
	s_add_u32 s3, s16, s4
	s_addc_u32 s4, s17, s5
	s_add_u32 s16, s3, s20
	v_and_b32_e32 v0, 0xfff, v228
	s_addc_u32 s17, s4, 0
	s_movk_i32 s20, 0x1000
	v_lshlrev_b32_e32 v0, 2, v0
	v_mov_b32_e32 v229, v1
	v_cmp_gt_u32_e32 vcc, s20, v228
	v_lshl_add_u64 v[16:17], s[16:17], 0, v[0:1]
	v_lshl_add_u64 v[2:3], v[228:229], 2, s[12:13]
	v_cndmask_b32_e32 v3, v17, v3, vcc
	v_cndmask_b32_e32 v2, v16, v2, vcc
	global_load_dword v34, v[2:3], off
	v_add_u32_e32 v2, 0x200, v228
	v_and_b32_e32 v0, 0xfff, v2
	v_lshlrev_b32_e32 v0, 2, v0
	v_mov_b32_e32 v3, v1
	v_cmp_gt_u32_e32 vcc, s20, v2
	v_lshl_add_u64 v[4:5], s[16:17], 0, v[0:1]
	v_lshl_add_u64 v[6:7], v[2:3], 2, s[12:13]
	v_cndmask_b32_e32 v5, v5, v7, vcc
	v_cndmask_b32_e32 v4, v4, v6, vcc
	global_load_dword v3, v[4:5], off
	v_add_u32_e32 v4, 0x400, v228
	v_and_b32_e32 v0, 0xfff, v4
	v_lshlrev_b32_e32 v0, 2, v0
	v_mov_b32_e32 v5, v1
	v_cmp_gt_u32_e32 vcc, s20, v4
	v_lshl_add_u64 v[6:7], s[16:17], 0, v[0:1]
	v_lshl_add_u64 v[8:9], v[4:5], 2, s[12:13]
	v_cndmask_b32_e32 v7, v7, v9, vcc
	v_cndmask_b32_e32 v6, v6, v8, vcc
	global_load_dword v5, v[6:7], off
	v_add_u32_e32 v6, 0x600, v228
	v_and_b32_e32 v0, 0xfff, v6
	v_lshlrev_b32_e32 v0, 2, v0
	v_mov_b32_e32 v7, v1
	v_cmp_gt_u32_e32 vcc, s20, v6
	v_lshl_add_u64 v[8:9], s[16:17], 0, v[0:1]
	v_lshl_add_u64 v[10:11], v[6:7], 2, s[12:13]
	v_cndmask_b32_e32 v9, v9, v11, vcc
	v_cndmask_b32_e32 v8, v8, v10, vcc
	global_load_dword v7, v[8:9], off
	v_add_u32_e32 v8, 0x800, v228
	v_and_b32_e32 v0, 0xfff, v8
	v_lshlrev_b32_e32 v0, 2, v0
	v_mov_b32_e32 v9, v1
	v_cmp_gt_u32_e32 vcc, s20, v8
	v_lshl_add_u64 v[10:11], s[16:17], 0, v[0:1]
	v_lshl_add_u64 v[12:13], v[8:9], 2, s[12:13]
	v_cndmask_b32_e32 v11, v11, v13, vcc
	v_cndmask_b32_e32 v10, v10, v12, vcc
	global_load_dword v9, v[10:11], off
	v_add_u32_e32 v10, 0xa00, v228
	v_and_b32_e32 v0, 0xfff, v10
	v_lshlrev_b32_e32 v0, 2, v0
	v_mov_b32_e32 v11, v1
	v_cmp_gt_u32_e32 vcc, s20, v10
	v_lshl_add_u64 v[12:13], s[16:17], 0, v[0:1]
	v_lshl_add_u64 v[14:15], v[10:11], 2, s[12:13]
	v_cndmask_b32_e32 v13, v13, v15, vcc
	v_cndmask_b32_e32 v12, v12, v14, vcc
	global_load_dword v11, v[12:13], off
	v_add_u32_e32 v12, 0xc00, v228
	v_and_b32_e32 v0, 0xfff, v12
	v_lshlrev_b32_e32 v0, 2, v0
	v_mov_b32_e32 v13, v1
	v_cmp_gt_u32_e32 vcc, s20, v12
	v_lshl_add_u64 v[14:15], s[16:17], 0, v[0:1]
	v_lshl_add_u64 v[18:19], v[12:13], 2, s[12:13]
	v_cndmask_b32_e32 v15, v15, v19, vcc
	v_cndmask_b32_e32 v14, v14, v18, vcc
	global_load_dword v13, v[14:15], off
	v_add_u32_e32 v14, 0xe00, v228
	v_and_b32_e32 v0, 0xfff, v14
	v_lshlrev_b32_e32 v0, 2, v0
	v_mov_b32_e32 v15, v1
	v_cmp_gt_u32_e32 vcc, s20, v14
	v_lshl_add_u64 v[18:19], s[16:17], 0, v[0:1]
	v_lshl_add_u64 v[20:21], v[14:15], 2, s[12:13]
	v_cndmask_b32_e32 v19, v19, v21, vcc
	v_cndmask_b32_e32 v18, v18, v20, vcc
	v_add_u32_e32 v0, 0x1000, v228
	s_movk_i32 s3, 0xefff
	global_load_dword v15, v[18:19], off
	v_cmp_lt_u32_e32 vcc, s3, v228
	v_lshl_add_u64 v[18:19], v[0:1], 2, s[12:13]
	v_ashrrev_i32_e32 v72, 6, v228
	v_cndmask_b32_e32 v17, v17, v19, vcc
	v_cndmask_b32_e32 v16, v16, v18, vcc
	global_load_dword v35, v[16:17], off
	v_add_u32_e32 v16, 0x1200, v228
	v_and_b32_e32 v17, 0xfff, v16
	v_lshlrev_b32_e32 v18, 2, v17
	v_mov_b32_e32 v19, v1
	v_mov_b32_e32 v17, v1
	v_cmp_gt_u32_e32 vcc, s20, v16
	v_lshl_add_u64 v[18:19], s[16:17], 0, v[18:19]
	v_lshl_add_u64 v[20:21], v[16:17], 2, s[12:13]
	v_cndmask_b32_e32 v19, v19, v21, vcc
	v_cndmask_b32_e32 v18, v18, v20, vcc
	global_load_dword v17, v[18:19], off
	v_add_u32_e32 v18, 0x1400, v228
	v_and_b32_e32 v19, 0xfff, v18
	v_lshlrev_b32_e32 v20, 2, v19
	v_mov_b32_e32 v21, v1
	v_mov_b32_e32 v19, v1
	v_cmp_gt_u32_e32 vcc, s20, v18
	v_lshl_add_u64 v[20:21], s[16:17], 0, v[20:21]
	v_lshl_add_u64 v[22:23], v[18:19], 2, s[12:13]
	v_cndmask_b32_e32 v21, v21, v23, vcc
	v_cndmask_b32_e32 v20, v20, v22, vcc
	global_load_dword v19, v[20:21], off
	v_add_u32_e32 v20, 0x1600, v228
	v_and_b32_e32 v21, 0xfff, v20
	v_lshlrev_b32_e32 v22, 2, v21
	v_mov_b32_e32 v23, v1
	v_mov_b32_e32 v21, v1
	v_cmp_gt_u32_e32 vcc, s20, v20
	v_lshl_add_u64 v[22:23], s[16:17], 0, v[22:23]
	v_lshl_add_u64 v[24:25], v[20:21], 2, s[12:13]
	v_cndmask_b32_e32 v23, v23, v25, vcc
	v_cndmask_b32_e32 v22, v22, v24, vcc
	global_load_dword v21, v[22:23], off
	v_add_u32_e32 v22, 0x1800, v228
	v_and_b32_e32 v23, 0xfff, v22
	v_lshlrev_b32_e32 v24, 2, v23
	v_mov_b32_e32 v25, v1
	v_mov_b32_e32 v23, v1
	v_cmp_gt_u32_e32 vcc, s20, v22
	v_lshl_add_u64 v[24:25], s[16:17], 0, v[24:25]
	v_lshl_add_u64 v[26:27], v[22:23], 2, s[12:13]
	v_cndmask_b32_e32 v25, v25, v27, vcc
	v_cndmask_b32_e32 v24, v24, v26, vcc
	global_load_dword v23, v[24:25], off
	v_add_u32_e32 v24, 0x1a00, v228
	v_and_b32_e32 v25, 0xfff, v24
	v_lshlrev_b32_e32 v26, 2, v25
	v_mov_b32_e32 v27, v1
	v_mov_b32_e32 v25, v1
	v_cmp_gt_u32_e32 vcc, s20, v24
	v_lshl_add_u64 v[26:27], s[16:17], 0, v[26:27]
	v_lshl_add_u64 v[28:29], v[24:25], 2, s[12:13]
	v_cndmask_b32_e32 v27, v27, v29, vcc
	v_cndmask_b32_e32 v26, v26, v28, vcc
	global_load_dword v25, v[26:27], off
	v_add_u32_e32 v26, 0x1c00, v228
	v_and_b32_e32 v27, 0xfff, v26
	v_lshlrev_b32_e32 v28, 2, v27
	v_mov_b32_e32 v29, v1
	v_mov_b32_e32 v27, v1
	v_cmp_gt_u32_e32 vcc, s20, v26
	v_lshl_add_u64 v[28:29], s[16:17], 0, v[28:29]
	v_lshl_add_u64 v[30:31], v[26:27], 2, s[12:13]
	v_cndmask_b32_e32 v29, v29, v31, vcc
	v_cndmask_b32_e32 v28, v28, v30, vcc
	global_load_dword v27, v[28:29], off
	v_add_u32_e32 v28, 0x1e00, v228
	v_and_b32_e32 v29, 0xfff, v28
	v_lshlrev_b32_e32 v30, 2, v29
	v_mov_b32_e32 v31, v1
	v_mov_b32_e32 v29, v1
	v_cmp_gt_u32_e32 vcc, s20, v28
	v_lshl_add_u64 v[30:31], s[16:17], 0, v[30:31]
	v_lshl_add_u64 v[32:33], v[28:29], 2, s[12:13]
	v_cndmask_b32_e32 v31, v31, v33, vcc
	v_cndmask_b32_e32 v30, v30, v32, vcc
	global_load_dword v29, v[30:31], off
	s_mov_b32 s5, 0xfffffc0
	v_and_or_b32 v31, v72, s5, v248
	s_movk_i32 s3, 0x90
	v_lshrrev_b32_e32 v32, 5, v228
	s_waitcnt vmcnt(15)
; __device__ __forceinline__ bf16_t f2bf(float f) { unsigned u = __float_as_uint(f); return (bf16_t)((u + 0x7fffu + ((u >> 16) & 1u)) >> 16); }
; __device__ __forceinline__ float softplusf(float x) { return fmaxf(x, 0.f) + log1pf(__expf(-fabsf(x))); }
; #define LAS __attribute__((address_space(3)))
; template <bool FINAL> __device__ __forceinline__ void lru_pass(int l, int bx, int G, const float* const* in, const bf16_t* LX, const bf16_t* LG, bf16_t* YL, float* APROD, float* HEND, LAS unsigned char* lds, int tid) {
;     ...
; #pragma unroll
;         for (int k = 0; k < 16; ++k) { const int i = tid + MEGA_THREADS * k, mat = i >> 12, d = (i >> 6) & 63, ee = i & 63; *(LAS bf16_t*)(lds + LRU_WT + (mat * 64 + ee) * 144 + d * 2) = f2bf(wv_[k]); } }
;     const float* cw = in[8] + (size_t)l * 4 * DM; const float w0 = cw[ch], w1 = cw[DM + ch], w2 = cw[2 * DM + ch], w3 = cw[3 * DM + ch], bc = in[9][l * DM + ch];
;     const float bA = in[11][l * DM + ch], bX = in[13][l * DM + ch], spl = softplusf(-in[14][l * DM + ch]);
	v_bfe_u32 v30, v34, 16, 1
	v_mul_lo_u32 v31, v31, s3
	v_and_b32_e32 v32, 0x7e, v32
	v_add3_u32 v30, v34, v30, s1
	v_add3_u32 v31, 0, v31, v32
	ds_write_b16_d16_hi v31, v30 offset:18432
	s_waitcnt vmcnt(14)
	v_bfe_u32 v30, v3, 16, 1
	v_add3_u32 v3, v3, v30, s1
	v_ashrrev_i32_e32 v30, 6, v2
	v_and_or_b32 v30, v30, s5, v248
	v_lshrrev_b32_e32 v2, 5, v2
	v_mul_lo_u32 v30, v30, s3
	v_and_b32_e32 v2, 0x7e, v2
	v_add3_u32 v2, 0, v30, v2
	ds_write_b16_d16_hi v2, v3 offset:18432
	v_ashrrev_i32_e32 v3, 6, v4
	v_and_or_b32 v3, v3, s5, v248
	v_lshrrev_b32_e32 v4, 5, v4
	s_waitcnt vmcnt(13)
	v_bfe_u32 v2, v5, 16, 1
	v_mul_lo_u32 v3, v3, s3
	v_and_b32_e32 v4, 0x7e, v4
	v_add3_u32 v2, v5, v2, s1
	v_add3_u32 v3, 0, v3, v4
	ds_write_b16_d16_hi v3, v2 offset:18432
	v_ashrrev_i32_e32 v3, 6, v6
	v_and_or_b32 v3, v3, s5, v248
	v_lshrrev_b32_e32 v4, 5, v6
	s_waitcnt vmcnt(12)
	v_bfe_u32 v2, v7, 16, 1
	v_mul_lo_u32 v3, v3, s3
	v_and_b32_e32 v4, 0x7e, v4
	v_add3_u32 v2, v7, v2, s1
	v_add3_u32 v3, 0, v3, v4
	ds_write_b16_d16_hi v3, v2 offset:18432
	v_ashrrev_i32_e32 v3, 6, v8
	v_and_or_b32 v3, v3, s5, v248
	v_lshrrev_b32_e32 v4, 5, v8
	s_waitcnt vmcnt(11)
	v_bfe_u32 v2, v9, 16, 1
	v_mul_lo_u32 v3, v3, s3
	v_and_b32_e32 v4, 0x7e, v4
	v_add3_u32 v2, v9, v2, s1
	v_add3_u32 v3, 0, v3, v4
	ds_write_b16_d16_hi v3, v2 offset:18432
	v_ashrrev_i32_e32 v3, 6, v10
	v_and_or_b32 v3, v3, s5, v248
	v_lshrrev_b32_e32 v4, 5, v10
	s_waitcnt vmcnt(10)
	v_bfe_u32 v2, v11, 16, 1
	v_mul_lo_u32 v3, v3, s3
	v_and_b32_e32 v4, 0x7e, v4
	v_add3_u32 v2, v11, v2, s1
	v_add3_u32 v3, 0, v3, v4
	ds_write_b16_d16_hi v3, v2 offset:18432
	v_ashrrev_i32_e32 v3, 6, v12
	v_and_or_b32 v3, v3, s5, v248
	v_lshrrev_b32_e32 v4, 5, v12
	s_waitcnt vmcnt(9)
	v_bfe_u32 v2, v13, 16, 1
	v_mul_lo_u32 v3, v3, s3
	v_and_b32_e32 v4, 0x7e, v4
	v_add3_u32 v2, v13, v2, s1
	v_add3_u32 v3, 0, v3, v4
	ds_write_b16_d16_hi v3, v2 offset:18432
	v_ashrrev_i32_e32 v3, 6, v14
	v_and_or_b32 v3, v3, s5, v248
	v_lshrrev_b32_e32 v4, 5, v14
	s_waitcnt vmcnt(8)
	v_bfe_u32 v2, v15, 16, 1
	v_mul_lo_u32 v3, v3, s3
	v_and_b32_e32 v4, 0x7e, v4
	v_ashrrev_i32_e32 v0, 6, v0
	v_add3_u32 v2, v15, v2, s1
	v_add3_u32 v3, 0, v3, v4
	v_and_or_b32 v0, v0, s5, v248
	ds_write_b16_d16_hi v3, v2 offset:18432
	s_waitcnt vmcnt(7)
	v_bfe_u32 v2, v35, 16, 1
	v_mul_lo_u32 v0, v0, s3
	v_add3_u32 v2, v35, v2, s1
	v_add3_u32 v0, 0, v0, v32
	ds_write_b16_d16_hi v0, v2 offset:18432
	v_ashrrev_i32_e32 v2, 6, v16
	v_and_or_b32 v2, v2, s5, v248
	v_lshrrev_b32_e32 v3, 5, v16
	s_waitcnt vmcnt(6)
	v_bfe_u32 v0, v17, 16, 1
	v_mul_lo_u32 v2, v2, s3
	v_and_b32_e32 v3, 0x7e, v3
	v_add3_u32 v0, v17, v0, s1
	v_add3_u32 v2, 0, v2, v3
	ds_write_b16_d16_hi v2, v0 offset:18432
	v_ashrrev_i32_e32 v2, 6, v18
	v_and_or_b32 v2, v2, s5, v248
	v_lshrrev_b32_e32 v3, 5, v18
	s_waitcnt vmcnt(5)
	v_bfe_u32 v0, v19, 16, 1
	v_mul_lo_u32 v2, v2, s3
	v_and_b32_e32 v3, 0x7e, v3
	v_add3_u32 v0, v19, v0, s1
	v_add3_u32 v2, 0, v2, v3
	ds_write_b16_d16_hi v2, v0 offset:18432
	v_ashrrev_i32_e32 v2, 6, v20
	v_and_or_b32 v2, v2, s5, v248
	v_lshrrev_b32_e32 v3, 5, v20
	s_waitcnt vmcnt(4)
	v_bfe_u32 v0, v21, 16, 1
	v_mul_lo_u32 v2, v2, s3
	v_and_b32_e32 v3, 0x7e, v3
	v_add3_u32 v0, v21, v0, s1
	v_add3_u32 v2, 0, v2, v3
	ds_write_b16_d16_hi v2, v0 offset:18432
	v_ashrrev_i32_e32 v2, 6, v22
	v_and_or_b32 v2, v2, s5, v248
	v_lshrrev_b32_e32 v3, 5, v22
	s_waitcnt vmcnt(3)
	v_bfe_u32 v0, v23, 16, 1
	v_mul_lo_u32 v2, v2, s3
	v_and_b32_e32 v3, 0x7e, v3
	v_add3_u32 v0, v23, v0, s1
	v_add3_u32 v2, 0, v2, v3
	ds_write_b16_d16_hi v2, v0 offset:18432
	v_ashrrev_i32_e32 v2, 6, v24
	v_and_or_b32 v2, v2, s5, v248
	v_lshrrev_b32_e32 v3, 5, v24
	s_waitcnt vmcnt(2)
	v_bfe_u32 v0, v25, 16, 1
	v_mul_lo_u32 v2, v2, s3
	v_and_b32_e32 v3, 0x7e, v3
	v_add3_u32 v0, v25, v0, s1
	v_add3_u32 v2, 0, v2, v3
	ds_write_b16_d16_hi v2, v0 offset:18432
	v_ashrrev_i32_e32 v2, 6, v26
	v_and_or_b32 v2, v2, s5, v248
	v_lshrrev_b32_e32 v3, 5, v26
	s_waitcnt vmcnt(1)
	v_bfe_u32 v0, v27, 16, 1
	v_mul_lo_u32 v2, v2, s3
	v_and_b32_e32 v3, 0x7e, v3
	v_add3_u32 v0, v27, v0, s1
	v_add3_u32 v2, 0, v2, v3
	ds_write_b16_d16_hi v2, v0 offset:18432
	v_ashrrev_i32_e32 v2, 6, v28
	v_and_or_b32 v2, v2, s5, v248
	v_lshrrev_b32_e32 v3, 5, v28
	s_waitcnt vmcnt(0)
	v_bfe_u32 v0, v29, 16, 1
	v_mul_lo_u32 v2, v2, s3
	v_and_b32_e32 v3, 0x7e, v3
	v_lshl_or_b32 v9, s2, 6, v248
	s_lshl_b64 s[2:3], s[22:23], 14
	v_add3_u32 v0, v29, v0, s1
	v_add3_u32 v2, 0, v2, v3
	s_add_u32 s2, s8, s2
	ds_write_b16_d16_hi v2, v0 offset:18432
	s_addc_u32 s3, s9, s3
	v_lshlrev_b32_e32 v0, 2, v9
	v_lshl_add_u64 v[2:3], s[2:3], 0, v[0:1]
	v_add_co_u32_e32 v4, vcc, s81, v2
	global_load_dword v73, v0, s[2:3]
	s_nop 0
	v_addc_co_u32_e32 v5, vcc, 0, v3, vcc
	s_movk_i32 s2, 0x3000
	v_add_co_u32_e32 v2, vcc, s2, v2
	v_lshl_or_b32 v0, s22, 10, v9
	s_nop 0
	v_addc_co_u32_e32 v3, vcc, 0, v3, vcc
	global_load_dword v74, v[4:5], off offset:-4096
	global_load_dword v75, v[4:5], off
	global_load_dword v76, v[2:3], off
	v_lshlrev_b64 v[2:3], 2, v[0:1]
	v_lshl_add_u64 v[4:5], s[10:11], 0, v[2:3]
	global_load_dword v77, v[4:5], off
	v_lshl_add_u64 v[4:5], s[14:15], 0, v[2:3]
	global_load_dword v78, v[4:5], off
	v_lshl_add_u64 v[4:5], s[18:19], 0, v[2:3]
	v_lshl_add_u64 v[2:3], s[6:7], 0, v[2:3]
	global_load_dword v79, v[4:5], off
	s_mov_b32 s2, s22
	global_load_dword v5, v[2:3], off
	v_writelane_b32 v254, s2, 51
	v_ashrrev_i32_e32 v2, 8, v228
	v_readlane_b32 s8, v255, 8
	v_writelane_b32 v254, s3, 52
	s_mov_b32 s2, 0xbfb8aa3b
	v_readlane_b32 s9, v255, 9
	s_mov_b32 s4, 0xfffffc0
	s_movk_i32 s14, 0x1000
	s_waitcnt vmcnt(0)
; __device__ __forceinline__ float softplusf(float x) { return fmaxf(x, 0.f) + log1pf(__expf(-fabsf(x))); }
; #define LAS __attribute__((address_space(3)))
; template <bool FINAL> __device__ __forceinline__ void lru_pass(int l, int bx, int G, const float* const* in, const bf16_t* LX, const bf16_t* LG, bf16_t* YL, float* APROD, float* HEND, LAS unsigned char* lds, int tid) {
;     ...
;     const float bA = in[11][l * DM + ch], bX = in[13][l * DM + ch], spl = softplusf(-in[14][l * DM + ch]);
;     if (FINAL) {
;         const int c0 = bx >> 4, tg = tid >> 6, b = tg >> 2, sg = tg & 3; LAS float* carP = (LAS float*)(lds + LRU_SEG) + 1024, *carH = carP + 512;
;         const int lo = sg == 0 ? 0 : c0 + 16 * (sg - 1), hi = c0 + 16 * sg; float A[16], Hc[16];
; #pragma unroll
;         for (int i = 0; i < 16; ++i) { const int cc = lo + i; const bool ok = cc < hi; const size_t si = ((size_t)b * LRU_NCH + (ok ? cc : 0)) * DM + ch; const float a_ = APROD[si], h_ = HEND[si]; A[i] = ok ? a_ : 1.f; Hc[i] = ok ? h_ : 0.f; }
;         float cp = 1.f, chh = 0.f;
; #pragma unroll
;         for (int i = 0; i < 16; ++i) { chh = A[i] * chh + Hc[i]; cp *= A[i]; }
	v_mul_f32_e64 v0, |v5|, s2
	v_exp_f32_e32 v4, v0
	s_mov_b32 s2, 0x3f2aaaab
	v_add_f32_e32 v6, 1.0, v4
	v_frexp_mant_f32_e32 v0, v6
	v_cmp_gt_f32_e64 s[6:7], s2, v0
	s_ashr_i32 s2, s90, 4
	v_bfe_u32 v0, v228, 6, 2
	v_lshl_add_u32 v14, v0, 4, s2
	v_add_u32_e32 v3, -16, v14
	v_cmp_ne_u32_e32 vcc, 0, v0
	v_readlane_b32 s2, v255, 6
	v_readlane_b32 s3, v255, 7
	v_cndmask_b32_e32 v15, 0, v3, vcc
	v_cmp_lt_i32_e32 vcc, v15, v14
	v_ashrrev_i32_e32 v3, 31, v2
	v_lshlrev_b64 v[2:3], 16, v[2:3]
	v_cndmask_b32_e32 v10, 0, v15, vcc
	v_ashrrev_i32_e32 v11, 31, v10
	v_or_b32_e32 v2, v2, v9
	v_lshlrev_b64 v[10:11], 10, v[10:11]
	v_lshl_add_u64 v[10:11], v[10:11], 0, v[2:3]
	v_lshlrev_b64 v[10:11], 2, v[10:11]
	v_lshl_add_u64 v[12:13], s[2:3], 0, v[10:11]
	v_lshl_add_u64 v[10:11], s[8:9], 0, v[10:11]
	global_load_dword v7, v[12:13], off
	global_load_dword v8, v[10:11], off
	v_add_u32_e32 v10, 1, v15
	v_lshlrev_b32_e32 v0, 6, v0
	s_waitcnt vmcnt(1)
	v_cndmask_b32_e32 v7, 1.0, v7, vcc
	s_waitcnt vmcnt(0)
	v_cndmask_b32_e32 v8, 0, v8, vcc
	v_cmp_lt_i32_e32 vcc, v10, v14
	v_fmac_f32_e32 v8, 0, v7
	s_nop 0
	v_cndmask_b32_e32 v10, 0, v10, vcc
	v_ashrrev_i32_e32 v11, 31, v10
	v_lshlrev_b64 v[10:11], 10, v[10:11]
	v_lshl_add_u64 v[10:11], v[10:11], 0, v[2:3]
	v_lshlrev_b64 v[10:11], 2, v[10:11]
	v_lshl_add_u64 v[12:13], s[2:3], 0, v[10:11]
	v_lshl_add_u64 v[10:11], s[8:9], 0, v[10:11]
	global_load_dword v12, v[12:13], off
	s_nop 0
	global_load_dword v10, v[10:11], off
	s_waitcnt vmcnt(1)
	v_cndmask_b32_e32 v16, 1.0, v12, vcc
	v_mul_f32_e32 v7, v7, v16
	s_waitcnt vmcnt(0)
	v_cndmask_b32_e32 v17, 0, v10, vcc
	v_add_u32_e32 v10, 2, v15
	v_cmp_lt_i32_e32 vcc, v10, v14
	v_fmac_f32_e32 v17, v8, v16
	s_nop 0
	v_cndmask_b32_e32 v10, 0, v10, vcc
	v_ashrrev_i32_e32 v11, 31, v10
	v_lshlrev_b64 v[10:11], 10, v[10:11]
	v_lshl_add_u64 v[10:11], v[10:11], 0, v[2:3]
	v_lshlrev_b64 v[10:11], 2, v[10:11]
	v_lshl_add_u64 v[12:13], s[2:3], 0, v[10:11]
	v_lshl_add_u64 v[10:11], s[8:9], 0, v[10:11]
	global_load_dword v12, v[12:13], off
	s_nop 0
	global_load_dword v10, v[10:11], off
	s_waitcnt vmcnt(1)
	v_cndmask_b32_e32 v18, 1.0, v12, vcc
	v_mul_f32_e32 v7, v7, v18
	s_waitcnt vmcnt(0)
	v_cndmask_b32_e32 v19, 0, v10, vcc
	v_add_u32_e32 v10, 3, v15
	v_cmp_lt_i32_e32 vcc, v10, v14
	v_fmac_f32_e32 v19, v17, v18
	v_mov_b32_e32 v17, v1
	v_cndmask_b32_e32 v10, 0, v10, vcc
	v_ashrrev_i32_e32 v11, 31, v10
	v_lshlrev_b64 v[10:11], 10, v[10:11]
	v_lshl_add_u64 v[10:11], v[10:11], 0, v[2:3]
	v_lshlrev_b64 v[10:11], 2, v[10:11]
	v_lshl_add_u64 v[12:13], s[2:3], 0, v[10:11]
	v_lshl_add_u64 v[10:11], s[8:9], 0, v[10:11]
	global_load_dword v12, v[12:13], off
	s_nop 0
	global_load_dword v10, v[10:11], off
	s_waitcnt vmcnt(1)
	v_cndmask_b32_e32 v20, 1.0, v12, vcc
	v_mul_f32_e32 v7, v7, v20
	s_waitcnt vmcnt(0)
	v_cndmask_b32_e32 v21, 0, v10, vcc
	v_add_u32_e32 v10, 4, v15
	v_cmp_lt_i32_e32 vcc, v10, v14
	v_fmac_f32_e32 v21, v19, v20
	v_mov_b32_e32 v19, v1
	v_cndmask_b32_e32 v10, 0, v10, vcc
	v_ashrrev_i32_e32 v11, 31, v10
	v_lshlrev_b64 v[10:11], 10, v[10:11]
	v_lshl_add_u64 v[10:11], v[10:11], 0, v[2:3]
	v_lshlrev_b64 v[10:11], 2, v[10:11]
	v_lshl_add_u64 v[12:13], s[2:3], 0, v[10:11]
	v_lshl_add_u64 v[10:11], s[8:9], 0, v[10:11]
	global_load_dword v12, v[12:13], off
	s_nop 0
	global_load_dword v10, v[10:11], off
	s_waitcnt vmcnt(1)
	v_cndmask_b32_e32 v22, 1.0, v12, vcc
	v_mul_f32_e32 v7, v7, v22
	s_waitcnt vmcnt(0)
	v_cndmask_b32_e32 v23, 0, v10, vcc
	v_add_u32_e32 v10, 5, v15
	v_cmp_lt_i32_e32 vcc, v10, v14
	v_fmac_f32_e32 v23, v21, v22
	v_mov_b32_e32 v21, v1
	v_cndmask_b32_e32 v10, 0, v10, vcc
	v_ashrrev_i32_e32 v11, 31, v10
	v_lshlrev_b64 v[10:11], 10, v[10:11]
	v_lshl_add_u64 v[10:11], v[10:11], 0, v[2:3]
	v_lshlrev_b64 v[10:11], 2, v[10:11]
	v_lshl_add_u64 v[12:13], s[2:3], 0, v[10:11]
	v_lshl_add_u64 v[10:11], s[8:9], 0, v[10:11]
	global_load_dword v12, v[12:13], off
	s_nop 0
	global_load_dword v10, v[10:11], off
	s_waitcnt vmcnt(1)
	v_cndmask_b32_e32 v24, 1.0, v12, vcc
	v_mul_f32_e32 v7, v7, v24
	s_waitcnt vmcnt(0)
	v_cndmask_b32_e32 v25, 0, v10, vcc
	v_add_u32_e32 v10, 6, v15
	v_cmp_lt_i32_e32 vcc, v10, v14
	v_fmac_f32_e32 v25, v23, v24
	v_mov_b32_e32 v23, v1
	v_cndmask_b32_e32 v10, 0, v10, vcc
	v_ashrrev_i32_e32 v11, 31, v10
	v_lshlrev_b64 v[10:11], 10, v[10:11]
	v_lshl_add_u64 v[10:11], v[10:11], 0, v[2:3]
	v_lshlrev_b64 v[10:11], 2, v[10:11]
	v_lshl_add_u64 v[12:13], s[2:3], 0, v[10:11]
	v_lshl_add_u64 v[10:11], s[8:9], 0, v[10:11]
	global_load_dword v12, v[12:13], off
	s_nop 0
	global_load_dword v10, v[10:11], off
	s_waitcnt vmcnt(1)
	v_cndmask_b32_e32 v26, 1.0, v12, vcc
	v_mul_f32_e32 v7, v7, v26
	s_waitcnt vmcnt(0)
	v_cndmask_b32_e32 v27, 0, v10, vcc
	v_add_u32_e32 v10, 7, v15
	v_cmp_lt_i32_e32 vcc, v10, v14
	v_fmac_f32_e32 v27, v25, v26
	v_mov_b32_e32 v25, v1
	v_cndmask_b32_e32 v10, 0, v10, vcc
	v_ashrrev_i32_e32 v11, 31, v10
	v_lshlrev_b64 v[10:11], 10, v[10:11]
	v_lshl_add_u64 v[10:11], v[10:11], 0, v[2:3]
	v_lshlrev_b64 v[10:11], 2, v[10:11]
	v_lshl_add_u64 v[12:13], s[2:3], 0, v[10:11]
	v_lshl_add_u64 v[10:11], s[8:9], 0, v[10:11]
	global_load_dword v12, v[12:13], off
	s_nop 0
	global_load_dword v10, v[10:11], off
	s_waitcnt vmcnt(1)
	v_cndmask_b32_e32 v28, 1.0, v12, vcc
	v_mul_f32_e32 v7, v7, v28
	s_waitcnt vmcnt(0)
	v_cndmask_b32_e32 v29, 0, v10, vcc
	v_add_u32_e32 v10, 8, v15
	v_cmp_lt_i32_e32 vcc, v10, v14
	v_fmac_f32_e32 v29, v27, v28
	v_mov_b32_e32 v27, v1
	v_cndmask_b32_e32 v10, 0, v10, vcc
	v_ashrrev_i32_e32 v11, 31, v10
	v_lshlrev_b64 v[10:11], 10, v[10:11]
	v_lshl_add_u64 v[10:11], v[10:11], 0, v[2:3]
	v_lshlrev_b64 v[10:11], 2, v[10:11]
	v_lshl_add_u64 v[12:13], s[2:3], 0, v[10:11]
	v_lshl_add_u64 v[10:11], s[8:9], 0, v[10:11]
	global_load_dword v12, v[12:13], off
	s_nop 0
	global_load_dword v10, v[10:11], off
	s_waitcnt vmcnt(1)
; #define LAS __attribute__((address_space(3)))
; template <bool FINAL> __device__ __forceinline__ void lru_pass(int l, int bx, int G, const float* const* in, const bf16_t* LX, const bf16_t* LG, bf16_t* YL, float* APROD, float* HEND, LAS unsigned char* lds, int tid) {
;     ...
;         const int c0 = bx >> 4, tg = tid >> 6, b = tg >> 2, sg = tg & 3; LAS float* carP = (LAS float*)(lds + LRU_SEG) + 1024, *carH = carP + 512;
;         const int lo = sg == 0 ? 0 : c0 + 16 * (sg - 1), hi = c0 + 16 * sg; float A[16], Hc[16];
; #pragma unroll
;         for (int i = 0; i < 16; ++i) { const int cc = lo + i; const bool ok = cc < hi; const size_t si = ((size_t)b * LRU_NCH + (ok ? cc : 0)) * DM + ch; const float a_ = APROD[si], h_ = HEND[si]; A[i] = ok ? a_ : 1.f; Hc[i] = ok ? h_ : 0.f; }
;         float cp = 1.f, chh = 0.f;
; #pragma unroll
;         for (int i = 0; i < 16; ++i) { chh = A[i] * chh + Hc[i]; cp *= A[i]; }
	v_cndmask_b32_e32 v30, 1.0, v12, vcc
	v_mul_f32_e32 v7, v7, v30
	s_waitcnt vmcnt(0)
	v_cndmask_b32_e32 v31, 0, v10, vcc
	v_add_u32_e32 v10, 9, v15
	v_cmp_lt_i32_e32 vcc, v10, v14
	v_fmac_f32_e32 v31, v29, v30
	s_nop 0
	v_cndmask_b32_e32 v10, 0, v10, vcc
	v_ashrrev_i32_e32 v11, 31, v10
	v_lshlrev_b64 v[10:11], 10, v[10:11]
	v_lshl_add_u64 v[10:11], v[10:11], 0, v[2:3]
	v_lshlrev_b64 v[10:11], 2, v[10:11]
	v_lshl_add_u64 v[12:13], s[2:3], 0, v[10:11]
	v_lshl_add_u64 v[10:11], s[8:9], 0, v[10:11]
	global_load_dword v12, v[12:13], off
	s_nop 0
	global_load_dword v10, v[10:11], off
	s_waitcnt vmcnt(1)
	v_cndmask_b32_e32 v32, 1.0, v12, vcc
	v_mul_f32_e32 v7, v7, v32
	s_waitcnt vmcnt(0)
	v_cndmask_b32_e32 v33, 0, v10, vcc
	v_add_u32_e32 v10, 10, v15
	v_cmp_lt_i32_e32 vcc, v10, v14
	v_fmac_f32_e32 v33, v31, v32
	v_mov_b32_e32 v31, v1
	v_cndmask_b32_e32 v10, 0, v10, vcc
	v_ashrrev_i32_e32 v11, 31, v10
	v_lshlrev_b64 v[10:11], 10, v[10:11]
	v_lshl_add_u64 v[10:11], v[10:11], 0, v[2:3]
	v_lshlrev_b64 v[10:11], 2, v[10:11]
	v_lshl_add_u64 v[12:13], s[2:3], 0, v[10:11]
	v_lshl_add_u64 v[10:11], s[8:9], 0, v[10:11]
	global_load_dword v12, v[12:13], off
	s_nop 0
	global_load_dword v10, v[10:11], off
	s_waitcnt vmcnt(1)
	v_cndmask_b32_e32 v34, 1.0, v12, vcc
	v_mul_f32_e32 v7, v7, v34
	s_waitcnt vmcnt(0)
	v_cndmask_b32_e32 v35, 0, v10, vcc
	v_add_u32_e32 v10, 11, v15
	v_cmp_lt_i32_e32 vcc, v10, v14
	v_fmac_f32_e32 v35, v33, v34
	s_nop 0
	v_cndmask_b32_e32 v10, 0, v10, vcc
	v_ashrrev_i32_e32 v11, 31, v10
	v_lshlrev_b64 v[10:11], 10, v[10:11]
	v_lshl_add_u64 v[10:11], v[10:11], 0, v[2:3]
	v_lshlrev_b64 v[10:11], 2, v[10:11]
	v_lshl_add_u64 v[12:13], s[2:3], 0, v[10:11]
	v_lshl_add_u64 v[10:11], s[8:9], 0, v[10:11]
	global_load_dword v12, v[12:13], off
	s_nop 0
	global_load_dword v10, v[10:11], off
	s_waitcnt vmcnt(1)
	v_cndmask_b32_e32 v36, 1.0, v12, vcc
	v_mul_f32_e32 v7, v7, v36
	s_waitcnt vmcnt(0)
	v_cndmask_b32_e32 v37, 0, v10, vcc
	v_add_u32_e32 v10, 12, v15
	v_cmp_lt_i32_e32 vcc, v10, v14
	v_fmac_f32_e32 v37, v35, v36
	s_nop 0
	v_cndmask_b32_e32 v10, 0, v10, vcc
	v_ashrrev_i32_e32 v11, 31, v10
	v_lshlrev_b64 v[10:11], 10, v[10:11]
	v_lshl_add_u64 v[10:11], v[10:11], 0, v[2:3]
	v_lshlrev_b64 v[10:11], 2, v[10:11]
	v_lshl_add_u64 v[12:13], s[2:3], 0, v[10:11]
	v_lshl_add_u64 v[10:11], s[8:9], 0, v[10:11]
	global_load_dword v12, v[12:13], off
	s_nop 0
	global_load_dword v10, v[10:11], off
	s_waitcnt vmcnt(1)
	v_cndmask_b32_e32 v38, 1.0, v12, vcc
	v_mul_f32_e32 v7, v7, v38
	s_waitcnt vmcnt(0)
	v_cndmask_b32_e32 v39, 0, v10, vcc
	v_add_u32_e32 v10, 13, v15
	v_cmp_lt_i32_e32 vcc, v10, v14
	v_fmac_f32_e32 v39, v37, v38
	s_nop 0
	v_cndmask_b32_e32 v10, 0, v10, vcc
	v_ashrrev_i32_e32 v11, 31, v10
	v_lshlrev_b64 v[10:11], 10, v[10:11]
	v_lshl_add_u64 v[10:11], v[10:11], 0, v[2:3]
	v_lshlrev_b64 v[10:11], 2, v[10:11]
	v_lshl_add_u64 v[12:13], s[2:3], 0, v[10:11]
	v_lshl_add_u64 v[10:11], s[8:9], 0, v[10:11]
	global_load_dword v12, v[12:13], off
	s_nop 0
	global_load_dword v10, v[10:11], off
	s_waitcnt vmcnt(1)
	v_cndmask_b32_e32 v40, 1.0, v12, vcc
	v_mul_f32_e32 v7, v7, v40
	s_waitcnt vmcnt(0)
	v_cndmask_b32_e32 v41, 0, v10, vcc
	v_add_u32_e32 v10, 14, v15
	v_cmp_lt_i32_e32 vcc, v10, v14
	v_fmac_f32_e32 v41, v39, v40
	s_nop 0
	v_cndmask_b32_e32 v10, 0, v10, vcc
	v_ashrrev_i32_e32 v11, 31, v10
	v_lshlrev_b64 v[10:11], 10, v[10:11]
	v_lshl_add_u64 v[10:11], v[10:11], 0, v[2:3]
	v_lshlrev_b64 v[10:11], 2, v[10:11]
	v_lshl_add_u64 v[12:13], s[2:3], 0, v[10:11]
	v_lshl_add_u64 v[10:11], s[8:9], 0, v[10:11]
	global_load_dword v12, v[12:13], off
	s_nop 0
	global_load_dword v10, v[10:11], off
	s_waitcnt vmcnt(1)
	v_cndmask_b32_e32 v12, 1.0, v12, vcc
	v_mul_f32_e32 v7, v7, v12
	s_waitcnt vmcnt(0)
	v_cndmask_b32_e32 v13, 0, v10, vcc
	v_add_u32_e32 v10, 15, v15
	v_cmp_lt_i32_e32 vcc, v10, v14
	v_fmac_f32_e32 v13, v41, v12
	v_mov_b32_e32 v15, v1
	v_cndmask_b32_e32 v10, 0, v10, vcc
	v_ashrrev_i32_e32 v11, 31, v10
	v_lshlrev_b64 v[10:11], 10, v[10:11]
	v_lshl_add_u64 v[2:3], v[10:11], 0, v[2:3]
	v_lshlrev_b64 v[2:3], 2, v[2:3]
	v_lshl_add_u64 v[10:11], s[2:3], 0, v[2:3]
	v_lshl_add_u64 v[2:3], s[8:9], 0, v[2:3]
	global_load_dword v10, v[10:11], off
	s_lshl_b32 s3, s90, 3
	global_load_dword v2, v[2:3], off
	s_ashr_i32 s2, s90, 10
	s_and_b32 s3, s3, 0x1f80
	v_mov_b32_e32 v11, v1
	s_waitcnt vmcnt(1)
	v_cndmask_b32_e32 v3, 1.0, v10, vcc
	s_waitcnt vmcnt(0)
; #define LAS __attribute__((address_space(3)))
; template <bool FINAL> __device__ __forceinline__ void lru_load(int it, int n, const bf16_t* __restrict__ LX, const bf16_t* __restrict__ LG, float (&xw)[19], float (&gl)[16], int tid) {
;     const int b = it >> 10, c = (it >> 4) & 63, e = tid & 63, tg = tid >> 6, ch = n * 64 + e, t0 = c * LRU_TK + tg * 16;
;     bf16_t raw[19];
; #pragma unroll
;     for (int j = 0; j < 19; ++j) { const int t = t0 + j - 3; raw[j] = LX[((size_t)b * SEQ + (t >= 0 ? t : 0)) * DM + ch]; }
;     bf16_t rawg[16];
;     if (FINAL) {
; #pragma unroll
;         for (int j = 0; j < 16; ++j) rawg[j] = LG[((size_t)b * SEQ + t0 + j) * DM + ch]; }
;     __builtin_amdgcn_sched_barrier(0);
; template <bool FINAL> __device__ __forceinline__ void lru_pass(int l, int bx, int G, const float* const* in, const bf16_t* LX, const bf16_t* LG, bf16_t* YL, float* APROD, float* HEND, LAS unsigned char* lds, int tid) {
;     ...
;         const int c0 = bx >> 4, tg = tid >> 6, b = tg >> 2, sg = tg & 3; LAS float* carP = (LAS float*)(lds + LRU_SEG) + 1024, *carH = carP + 512;
;         const int lo = sg == 0 ? 0 : c0 + 16 * (sg - 1), hi = c0 + 16 * sg; float A[16], Hc[16];
; #pragma unroll
;         for (int i = 0; i < 16; ++i) { const int cc = lo + i; const bool ok = cc < hi; const size_t si = ((size_t)b * LRU_NCH + (ok ? cc : 0)) * DM + ch; const float a_ = APROD[si], h_ = HEND[si]; A[i] = ok ? a_ : 1.f; Hc[i] = ok ? h_ : 0.f; }
;         float cp = 1.f, chh = 0.f;
; #pragma unroll
;         for (int i = 0; i < 16; ++i) { chh = A[i] * chh + Hc[i]; cp *= A[i]; }
;         carP[(b * 4 + sg) * 64 + e] = cp; carH[(b * 4 + sg) * 64 + e] = chh;
;     }
;     float xwn[19], gln[16];
; #pragma unroll
;     for (int j = 0; j < 16; ++j) gln[j] = 0.f;
;     lru_load<FINAL>(bx, n, LX, LG, xwn, gln, tid);
;     __syncthreads();
	v_cndmask_b32_e32 v2, 0, v2, vcc
	v_fmac_f32_e32 v2, v13, v3
	v_mul_f32_e32 v3, v7, v3
	v_and_b32_e32 v7, 0xffffff00, v228
	v_or3_b32 v0, v0, v7, v248
	v_lshl_add_u32 v0, v0, 2, 0
	v_add_u32_e32 v8, 0x1a800, v0
	ds_write_b32 v8, v3
	v_ashrrev_i32_e32 v8, 2, v228
	v_add_u32_e32 v0, 0x1b000, v0
	v_and_b32_e32 v80, -16, v8
	ds_write_b32 v0, v2
	v_add_u32_e32 v2, s3, v80
	s_ashr_i32 s3, s2, 31
	s_lshl_b64 s[8:9], s[2:3], 24
	v_readlane_b32 s2, v255, 4
	v_readlane_b32 s3, v255, 5
	s_add_u32 s2, s2, s8
	v_max_i32_e32 v3, 3, v2
	s_addc_u32 s3, s3, s9
	v_lshlrev_b32_e32 v0, 1, v9
	v_add_u32_e32 v10, -3, v3
	v_lshl_add_u64 v[28:29], s[2:3], 0, v[0:1]
	v_lshlrev_b64 v[10:11], 11, v[10:11]
	v_or_b32_e32 v3, 1, v2
	v_lshl_add_u64 v[10:11], v[28:29], 0, v[10:11]
	v_max_i32_e32 v3, 3, v3
	global_load_ushort v9, v[10:11], off
	v_add_u32_e32 v10, -3, v3
	v_or_b32_e32 v3, 2, v2
	v_max_i32_e32 v3, 3, v3
	v_mov_b32_e32 v11, v1
	v_add_u32_e32 v12, -3, v3
	v_mov_b32_e32 v13, v1
	v_lshlrev_b64 v[10:11], 11, v[10:11]
	v_lshlrev_b64 v[12:13], 11, v[12:13]
	v_or_b32_e32 v3, 3, v2
	v_lshl_add_u64 v[10:11], v[28:29], 0, v[10:11]
	v_lshl_add_u64 v[12:13], v[28:29], 0, v[12:13]
	v_max_i32_e32 v3, 3, v3
	global_load_ushort v10, v[10:11], off
	s_mov_b64 s[2:3], 0xa100000
	global_load_ushort v11, v[12:13], off
	v_add_u32_e32 v12, -3, v3
	v_or_b32_e32 v3, 4, v2
	v_max_i32_e32 v3, 3, v3
	v_mov_b32_e32 v13, v1
	v_add_u32_e32 v14, -3, v3
	v_lshlrev_b64 v[12:13], 11, v[12:13]
	v_lshlrev_b64 v[14:15], 11, v[14:15]
	v_or_b32_e32 v3, 5, v2
	v_lshl_add_u64 v[12:13], v[28:29], 0, v[12:13]
	v_lshl_add_u64 v[14:15], v[28:29], 0, v[14:15]
	v_max_i32_e32 v3, 3, v3
	global_load_ushort v12, v[12:13], off
	s_nop 0
	global_load_ushort v13, v[14:15], off
	v_add_u32_e32 v14, -3, v3
	v_or_b32_e32 v3, 6, v2
	v_max_i32_e32 v3, 3, v3
	v_mov_b32_e32 v15, v1
	v_add_u32_e32 v16, -3, v3
	v_lshlrev_b64 v[14:15], 11, v[14:15]
	v_lshlrev_b64 v[16:17], 11, v[16:17]
	v_or_b32_e32 v3, 7, v2
	v_lshl_add_u64 v[14:15], v[28:29], 0, v[14:15]
	v_lshl_add_u64 v[16:17], v[28:29], 0, v[16:17]
	v_max_i32_e32 v3, 3, v3
	global_load_ushort v14, v[14:15], off
	s_nop 0
	global_load_ushort v15, v[16:17], off
	v_add_u32_e32 v16, -3, v3
	v_or_b32_e32 v3, 8, v2
	v_max_i32_e32 v3, 3, v3
	v_mov_b32_e32 v17, v1
	v_add_u32_e32 v18, -3, v3
	v_lshlrev_b64 v[16:17], 11, v[16:17]
	v_lshlrev_b64 v[18:19], 11, v[18:19]
	v_or_b32_e32 v3, 9, v2
	v_lshl_add_u64 v[16:17], v[28:29], 0, v[16:17]
	v_lshl_add_u64 v[18:19], v[28:29], 0, v[18:19]
	v_max_i32_e32 v3, 3, v3
	global_load_ushort v17, v[16:17], off
	s_nop 0
	global_load_ushort v16, v[18:19], off
	v_add_u32_e32 v18, -3, v3
	v_or_b32_e32 v3, 10, v2
	v_max_i32_e32 v3, 3, v3
	v_mov_b32_e32 v19, v1
	v_add_u32_e32 v20, -3, v3
	v_lshlrev_b64 v[18:19], 11, v[18:19]
	v_lshlrev_b64 v[20:21], 11, v[20:21]
	v_or_b32_e32 v3, 11, v2
	v_lshl_add_u64 v[18:19], v[28:29], 0, v[18:19]
	v_lshl_add_u64 v[20:21], v[28:29], 0, v[20:21]
	v_max_i32_e32 v3, 3, v3
	global_load_ushort v18, v[18:19], off
	s_nop 0
	global_load_ushort v19, v[20:21], off
	v_add_u32_e32 v20, -3, v3
	v_or_b32_e32 v3, 12, v2
	v_max_i32_e32 v3, 3, v3
	v_mov_b32_e32 v21, v1
	v_add_u32_e32 v22, -3, v3
	v_lshlrev_b64 v[20:21], 11, v[20:21]
	v_lshlrev_b64 v[22:23], 11, v[22:23]
	v_or_b32_e32 v3, 13, v2
	v_lshl_add_u64 v[20:21], v[28:29], 0, v[20:21]
	v_lshl_add_u64 v[22:23], v[28:29], 0, v[22:23]
	v_max_i32_e32 v3, 3, v3
	global_load_ushort v20, v[20:21], off
	s_nop 0
	global_load_ushort v21, v[22:23], off
	v_add_u32_e32 v22, -3, v3
	v_or_b32_e32 v3, 14, v2
	v_max_i32_e32 v3, 3, v3
	v_mov_b32_e32 v23, v1
	v_add_u32_e32 v24, -3, v3
	v_lshlrev_b64 v[22:23], 11, v[22:23]
	v_lshlrev_b64 v[24:25], 11, v[24:25]
	v_or_b32_e32 v3, 15, v2
	v_lshl_add_u64 v[22:23], v[28:29], 0, v[22:23]
	v_lshl_add_u64 v[24:25], v[28:29], 0, v[24:25]
	v_max_i32_e32 v3, 3, v3
	global_load_ushort v22, v[22:23], off
	s_nop 0
	global_load_ushort v23, v[24:25], off
	v_add_u32_e32 v24, -3, v3
	v_max_i32_e32 v3, -13, v2
	v_mov_b32_e32 v25, v1
	v_add_u32_e32 v26, 13, v3
	v_lshlrev_b64 v[24:25], 11, v[24:25]
	v_lshlrev_b64 v[26:27], 11, v[26:27]
	v_lshl_add_u64 v[24:25], v[28:29], 0, v[24:25]
	v_lshl_add_u64 v[26:27], v[28:29], 0, v[26:27]
	v_max_i32_e32 v3, -14, v2
	global_load_ushort v25, v[24:25], off
	s_nop 0
	global_load_ushort v24, v[26:27], off
	v_add_u32_e32 v26, 14, v3
	v_max_i32_e32 v3, -15, v2
	v_mov_b32_e32 v27, v1
	v_add_u32_e32 v30, 15, v3
	v_lshlrev_b64 v[26:27], 11, v[26:27]
	v_lshlrev_b64 v[30:31], 11, v[30:31]
	v_lshl_add_u64 v[26:27], v[28:29], 0, v[26:27]
	v_lshl_add_u64 v[28:29], v[28:29], 0, v[30:31]
	v_lshl_add_u64 v[30:31], s[76:77], 0, v[0:1]
	v_ashrrev_i32_e32 v3, 31, v2
	v_lshl_add_u64 v[34:35], v[30:31], 0, s[2:3]
	v_lshlrev_b64 v[30:31], 11, v[2:3]
	v_lshl_add_u64 v[32:33], v[34:35], 0, s[8:9]
	v_lshl_add_u64 v[36:37], v[32:33], 0, v[30:31]
	v_add_co_u32_e32 v30, vcc, s20, v36
	global_load_ushort v27, v[26:27], off
	s_nop 0
	v_addc_co_u32_e32 v31, vcc, 0, v37, vcc
	v_add_co_u32_e32 v32, vcc, s81, v36
	global_load_ushort v29, v[28:29], off
	s_nop 0
	v_addc_co_u32_e32 v33, vcc, 0, v37, vcc
	v_add_co_u32_e32 v38, vcc, 0x3000, v36
	global_load_ushort v3, v[36:37], off
	global_load_ushort v26, v[36:37], off offset:2048
	v_addc_co_u32_e32 v39, vcc, 0, v37, vcc
	global_load_ushort v28, v[32:33], off offset:-4096
	s_nop 0
	global_load_ushort v30, v[30:31], off offset:2048
	s_nop 0
	global_load_ushort v31, v[32:33], off
	s_nop 0
	global_load_ushort v32, v[32:33], off offset:2048
	s_nop 0
	global_load_ushort v33, v[38:39], off
	global_load_ushort v42, v[38:39], off offset:2048
	v_add_co_u32_e32 v38, vcc, s79, v36
	s_movk_i32 s2, 0x5000
	s_nop 0
	v_addc_co_u32_e32 v39, vcc, 0, v37, vcc
	v_add_co_u32_e32 v40, vcc, s2, v36
	s_nop 1
	v_addc_co_u32_e32 v41, vcc, 0, v37, vcc
	global_load_ushort v43, v[40:41], off offset:-4096
	global_load_ushort v46, v[38:39], off offset:2048
	global_load_ushort v44, v[40:41], off
	global_load_ushort v47, v[40:41], off offset:2048
	v_add_co_u32_e32 v38, vcc, 0x6000, v36
	s_nop 1
	v_addc_co_u32_e32 v39, vcc, 0, v37, vcc
	v_add_co_u32_e32 v36, vcc, 0x7000, v36
	global_load_ushort v40, v[38:39], off
	global_load_ushort v45, v[38:39], off offset:2048
	v_addc_co_u32_e32 v37, vcc, 0, v37, vcc
	global_load_ushort v38, v[36:37], off
	global_load_ushort v41, v[36:37], off offset:2048
	s_cmpk_gt_i32 s90, 0x7ff
	s_waitcnt lgkmcnt(0)
	s_barrier
; __device__ __forceinline__ float softplusf(float x) { return fmaxf(x, 0.f) + log1pf(__expf(-fabsf(x))); }
; template <bool FINAL> __device__ __forceinline__ void lru_pass(int l, int bx, int G, const float* const* in, const bf16_t* LX, const bf16_t* LG, bf16_t* YL, float* APROD, float* HEND, LAS unsigned char* lds, int tid) {
;     ...
;     const float bA = in[11][l * DM + ch], bX = in[13][l * DM + ch], spl = softplusf(-in[14][l * DM + ch]);
	s_cbranch_scc1 .LBB9_426
	v_add_f32_e32 v36, -1.0, v6
	v_sub_f32_e32 v37, v36, v6
	v_add_f32_e32 v37, 1.0, v37
	v_sub_f32_e32 v36, v4, v36
	v_add_f32_e32 v39, v36, v37
	v_cvt_f64_f32_e32 v[36:37], v6
	v_frexp_exp_i32_f64_e32 v36, v[36:37]
	v_subbrev_co_u32_e64 v36, vcc, 0, v36, s[6:7]
	v_sub_u32_e32 v37, 0, v36
	v_ldexp_f32 v6, v6, v37
	v_ldexp_f32 v37, v39, v37
	v_add_f32_e32 v39, -1.0, v6
	v_add_f32_e32 v50, 1.0, v6
	v_add_f32_e32 v48, 1.0, v39
	v_add_f32_e32 v51, -1.0, v50
	v_sub_f32_e32 v48, v6, v48
	v_sub_f32_e32 v6, v6, v51
	v_add_f32_e32 v6, v37, v6
	v_add_f32_e32 v48, v37, v48
	v_add_f32_e32 v37, v50, v6
	v_rcp_f32_e32 v51, v37
	v_add_f32_e32 v49, v39, v48
	v_sub_f32_e32 v39, v49, v39
	v_sub_f32_e32 v39, v48, v39
	v_sub_f32_e32 v48, v37, v50
	v_sub_f32_e32 v6, v6, v48
	v_mul_f32_e32 v48, v49, v51
	v_mul_f32_e32 v50, v37, v48
	v_fma_f32 v52, v48, v37, -v50
	v_fmac_f32_e32 v52, v48, v6
	v_add_f32_e32 v53, v50, v52
	v_sub_f32_e32 v54, v49, v53
	v_sub_f32_e32 v49, v49, v54
	v_sub_f32_e32 v50, v53, v50
	v_sub_f32_e32 v49, v49, v53
	v_add_f32_e32 v39, v39, v49
	v_sub_f32_e32 v49, v50, v52
	v_add_f32_e32 v39, v49, v39
	v_add_f32_e32 v49, v54, v39
	v_mul_f32_e32 v50, v51, v49
	v_mul_f32_e32 v52, v37, v50
	v_fma_f32 v37, v50, v37, -v52
	v_fmac_f32_e32 v37, v50, v6
	v_sub_f32_e32 v6, v54, v49
	v_add_f32_e32 v6, v39, v6
	v_add_f32_e32 v39, v52, v37
	v_sub_f32_e32 v53, v49, v39
	v_sub_f32_e32 v49, v49, v53
	v_sub_f32_e32 v52, v39, v52
	v_sub_f32_e32 v39, v49, v39
	v_add_f32_e32 v6, v6, v39
	v_sub_f32_e32 v37, v52, v37
	v_add_f32_e32 v6, v37, v6
	v_add_f32_e32 v37, v48, v50
	v_cvt_f32_i32_e32 v36, v36
	v_add_f32_e32 v6, v53, v6
	v_sub_f32_e32 v39, v37, v48
	v_mul_f32_e32 v6, v51, v6
	v_sub_f32_e32 v39, v50, v39
	v_add_f32_e32 v6, v39, v6
	v_add_f32_e32 v39, v37, v6
	v_mul_f32_e32 v50, 0x3f317218, v36
	s_mov_b32 s2, 0x3f317218
	v_mul_f32_e32 v48, v39, v39
	v_fma_f32 v51, v36, s2, -v50
	v_fmamk_f32 v49, v48, 0x3e9b6dac, v237
	v_fmac_f32_e32 v51, 0xb102e308, v36
	v_sub_f32_e32 v36, v39, v37
	v_fmaak_f32 v49, v48, v49, 0x3f2aaada
	v_sub_f32_e32 v6, v6, v36
	v_ldexp_f32 v36, v39, 1
	v_mul_f32_e32 v39, v39, v48
	v_mul_f32_e32 v39, v39, v49
	v_add_f32_e32 v48, v36, v39
	v_sub_f32_e32 v36, v48, v36
	v_ldexp_f32 v6, v6, 1
	v_sub_f32_e32 v36, v39, v36
	v_add_f32_e32 v6, v6, v36
	v_add_f32_e32 v36, v48, v6
	v_add_f32_e32 v52, v50, v51
	v_sub_f32_e32 v39, v36, v48
	v_sub_f32_e32 v6, v6, v39
	v_add_f32_e32 v39, v52, v36
	v_sub_f32_e32 v48, v39, v52
	v_sub_f32_e32 v50, v52, v50
	v_sub_f32_e32 v49, v39, v48
	v_sub_f32_e32 v50, v51, v50
	v_sub_f32_e32 v49, v52, v49
	v_sub_f32_e32 v36, v36, v48
	v_add_f32_e32 v36, v36, v49
	v_add_f32_e32 v48, v50, v6
	v_sub_f32_e32 v49, v48, v50
	v_add_f32_e32 v36, v48, v36
	v_sub_f32_e32 v51, v48, v49
	v_add_f32_e32 v48, v39, v36
	v_sub_f32_e32 v50, v50, v51
	v_sub_f32_e32 v6, v6, v49
	v_sub_f32_e32 v39, v48, v39
	v_add_f32_e32 v6, v6, v50
	v_sub_f32_e32 v36, v36, v39
	v_add_f32_e32 v6, v6, v36
	s_mov_b32 s2, 0x7f800000
	v_add_f32_e32 v6, v48, v6
	v_cmp_neq_f32_e32 vcc, s2, v4
	v_and_b32_e32 v37, 0x7fffffff, v4
	s_mov_b32 s2, 0x33800000
	v_cndmask_b32_e32 v6, v246, v6, vcc
	v_cmp_ngt_f32_e32 vcc, -1.0, v4
	v_max_f32_e64 v5, -v5, -v5
	v_max_f32_e32 v5, 0, v5
	v_cndmask_b32_e32 v6, v247, v6, vcc
	v_cmp_neq_f32_e32 vcc, -1.0, v4
	s_waitcnt vmcnt(15)
	v_lshlrev_b32_e32 v55, 16, v3
	v_lshlrev_b32_e32 v3, 16, v10
	v_cndmask_b32_e32 v6, v245, v6, vcc
	v_cmp_gt_f32_e32 vcc, s2, v37
	s_waitcnt vmcnt(9)
; #define LAS __attribute__((address_space(3)))
; template <bool FINAL> __device__ __forceinline__ void lru_item(int b, int c, int n, const float (&xw)[19], const float (&gl)[16], bf16_t* __restrict__ YL, ...
;     const int e = tid & 63, tg = tid >> 6, ch = n * 64 + e, lane = e, wv = tg;
;     LAS float* R = (LAS float*)(lds + LRU_R);
;     LAS float* segP = (LAS float*)(lds + LRU_SEG);
;     LAS float* segH = segP + 512, *carP = segH + 512 + (b * 4) * 64, *carH = carP + 512;
;     const int t0 = c * LRU_TK + tg * 16; const size_t row0 = (size_t)b * SEQ + t0;
;     float xc[16];
; #pragma unroll
;     for (int j = 0; j < 16; ++j) { xc[j] = bc + w3 * xw[j + 3] + w2 * xw[j + 2] + w1 * xw[j + 1] + w0 * xw[j]; *(LAS bf16_t*)(lds + LRU_XCB + (tg * 16 + j) * 144 + e * 2) = f2bf(xc[j]); }
;     LDS_BAR();
;     { const int tq = wv & 3, cbh = wv >> 2, r32 = lane & 31, hi = lane >> 5; f32x16_t acc0 = {}, acc1 = {};
; #pragma unroll
;         for (int ks = 0; ks < 4; ++ks) { const bf16x8_t af = *(const LAS bf16x8_t*)(lds + LRU_XCB + (32 * tq + r32) * 144 + (16 * ks + 8 * hi) * 2);
;             const bf16x8_t b0 = *(const LAS bf16x8_t*)(lds + LRU_WT + (64 * cbh + r32) * 144 + (16 * ks + 8 * hi) * 2), b1 = *(const LAS bf16x8_t*)(lds + LRU_WT + (64 * cbh + 32 + r32) * 144 + (16 * ks + 8 * hi) * 2);
;             acc0 = __builtin_amdgcn_mfma_f32_32x32x16_bf16(af, b0, acc0, 0, 0, 0); acc1 = __builtin_amdgcn_mfma_f32_32x32x16_bf16(af, b1, acc1, 0, 0, 0); }
; #pragma unroll
; template <bool FINAL> __device__ __forceinline__ void lru_pass(int l, int bx, int G, const float* const* in, const bf16_t* LX, const bf16_t* LG, bf16_t* YL, float* APROD, float* HEND, LAS unsigned char* lds, int tid) {
;     ...
;     float xwn[19], gln[16];
; #pragma unroll
;     for (int j = 0; j < 16; ++j) gln[j] = 0.f;
;     lru_load<FINAL>(bx, n, LX, LG, xwn, gln, tid);
;     __syncthreads();
;     for (int it = bx; it < 2048; it += G) {
;         float xw[19], gl[16];
; #pragma unroll
;         for (int j = 0; j < 19; ++j) xw[j] = xwn[j];
; #pragma unroll
;         for (int j = 0; j < 16; ++j) gl[j] = gln[j];
;         if (it + G < 2048) lru_load<FINAL>(it + G, n, LX, LG, xwn, gln, tid);
;         lru_item<FINAL>(it >> 10, (it >> 4) & 63, n, xw, gl, YL, w0, w1, w2, w3, bc, bA, bX, spl, APROD, HEND, lds, tid, ((it >> 4) & 63) >> 4);
	v_lshlrev_b32_e32 v49, 16, v33
	v_lshlrev_b32_e32 v50, 16, v32
	v_cndmask_b32_e32 v4, v6, v4, vcc
	v_add_f32_e32 v81, v5, v4
	v_lshlrev_b32_e32 v4, 16, v9
	v_cmp_lt_i32_e32 vcc, 2, v2
	v_lshlrev_b32_e32 v51, 16, v31
	v_lshlrev_b32_e32 v52, 16, v30
	v_cndmask_b32_e32 v126, 0, v4, vcc
	v_cmp_lt_i32_e32 vcc, 1, v2
	v_lshlrev_b32_e32 v4, 16, v11
	v_lshlrev_b32_e32 v53, 16, v28
	v_cndmask_b32_e32 v33, 0, v3, vcc
	v_cmp_lt_i32_e32 vcc, 0, v2
	v_lshlrev_b32_e32 v3, 16, v12
	v_lshlrev_b32_e32 v54, 16, v26
	v_cndmask_b32_e32 v32, 0, v4, vcc
	v_cmp_lt_i32_e32 vcc, -1, v2
	v_lshlrev_b32_e32 v4, 16, v13
	v_readlane_b32 s2, v255, 4
	v_cndmask_b32_e32 v31, 0, v3, vcc
	v_cmp_lt_i32_e32 vcc, -2, v2
	v_lshlrev_b32_e32 v3, 16, v14
	v_lshlrev_b32_e32 v6, 16, v24
	v_cndmask_b32_e32 v30, 0, v4, vcc
	v_cmp_lt_i32_e32 vcc, -3, v2
	v_lshlrev_b32_e32 v4, 16, v15
	v_readlane_b32 s3, v255, 5
	v_cndmask_b32_e32 v28, 0, v3, vcc
	v_cmp_lt_i32_e32 vcc, -4, v2
	v_lshlrev_b32_e32 v3, 16, v17
	v_lshl_add_u64 v[36:37], s[2:3], 0, v[0:1]
	v_cndmask_b32_e32 v26, 0, v4, vcc
	v_cmp_lt_i32_e32 vcc, -5, v2
	v_lshlrev_b32_e32 v4, 16, v16
	v_lshlrev_b32_e32 v82, 4, v72
	v_cndmask_b32_e32 v17, 0, v3, vcc
	v_cmp_lt_i32_e32 vcc, -6, v2
	v_lshlrev_b32_e32 v3, 16, v18
	s_movk_i32 s2, 0x900
	v_cndmask_b32_e32 v16, 0, v4, vcc
	v_cmp_lt_i32_e32 vcc, -7, v2
	v_lshlrev_b32_e32 v4, 16, v19
	v_or_b32_e32 v18, 1, v82
	v_cndmask_b32_e32 v15, 0, v3, vcc
	v_cmp_lt_i32_e32 vcc, -8, v2
	v_lshlrev_b32_e32 v3, 16, v20
	v_and_b32_e32 v20, 31, v228
	v_cndmask_b32_e32 v14, 0, v4, vcc
	v_cmp_lt_i32_e32 vcc, -9, v2
	v_lshlrev_b32_e32 v4, 16, v21
	v_and_or_b32 v8, v8, s4, v20
	v_cndmask_b32_e32 v12, 0, v3, vcc
	v_cmp_lt_i32_e32 vcc, -10, v2
	v_lshlrev_b32_e32 v3, 16, v22
	v_lshlrev_b32_e32 v22, 5, v72
	v_cndmask_b32_e32 v11, 0, v4, vcc
	v_cmp_lt_i32_e32 vcc, -11, v2
	v_lshlrev_b32_e32 v4, 16, v23
	v_and_b32_e32 v22, 0x60, v22
	v_cndmask_b32_e32 v9, 0, v3, vcc
	v_cmp_lt_i32_e32 vcc, -12, v2
	v_lshlrev_b32_e32 v3, 16, v25
	v_or_b32_e32 v23, v22, v20
	v_cndmask_b32_e32 v5, 0, v4, vcc
	v_cmp_lt_i32_e32 vcc, -13, v2
	v_lshrrev_b32_e32 v21, 5, v248
	v_lshlrev_b32_e32 v20, 2, v20
	v_cndmask_b32_e32 v4, 0, v3, vcc
	v_cmp_lt_i32_e32 vcc, -14, v2
	v_lshlrev_b32_e32 v3, 16, v27
	v_lshlrev_b32_e32 v24, 4, v21
	v_cndmask_b32_e32 v6, 0, v6, vcc
	v_cmp_lt_i32_e32 vcc, -15, v2
	v_add3_u32 v7, 0, v7, v20
	v_lshl_or_b32 v20, v21, 2, v22
	v_cndmask_b32_e32 v10, 0, v3, vcc
	v_lshlrev_b32_e32 v3, 16, v29
	v_cmp_lt_i32_e32 vcc, -16, v2
	v_lshlrev_b32_e32 v22, 2, v248
	v_readlane_b32 s4, v254, 53
	v_cndmask_b32_e32 v13, 0, v3, vcc
	v_mul_lo_u32 v3, v72, s2
	s_movk_i32 s2, 0x90
	v_mul_lo_u32 v19, v18, s2
	v_mad_u32_u24 v23, v23, s2, 0
	v_mul_lo_u32 v8, v8, s2
	s_movk_i32 s2, 0x2100
	v_mul_lo_u32 v21, v72, s2
	s_movk_i32 s2, 0x210
	v_mul_lo_u32 v18, v18, s2
	v_add3_u32 v84, 0, v18, v22
	v_lshlrev_b32_e32 v18, 2, v228
	v_readlane_b32 s2, v254, 22
	s_waitcnt vmcnt(1)
	v_lshlrev_b32_e32 v39, 16, v38
	s_waitcnt vmcnt(0)
	v_lshlrev_b32_e32 v38, 16, v41
	v_lshlrev_b32_e32 v41, 16, v40
	v_lshlrev_b32_e32 v40, 16, v45
	v_lshlrev_b32_e32 v45, 16, v44
	v_lshlrev_b32_e32 v44, 16, v47
	v_lshlrev_b32_e32 v47, 16, v43
	v_lshlrev_b32_e32 v46, 16, v46
	v_lshlrev_b32_e32 v48, 16, v42
	v_lshl_add_u32 v2, v248, 1, 0
	v_add_u32_e32 v8, 0, v8
	v_mul_u32_u24_e32 v20, 0x210, v20
	v_add_u32_e32 v99, s2, v18
	s_add_i32 s2, 0, 0x1a000
	v_readlane_b32 s5, v254, 54
	s_add_i32 s3, 0, 0x1b000
	v_add3_u32 v83, 0, v21, v22
	v_add_u32_e32 v85, 0x210, v84
	v_add_u32_e32 v86, 0x420, v84
	v_add_u32_e32 v87, 0x630, v84
	v_add_u32_e32 v88, 0x840, v84
	v_add_u32_e32 v89, 0xa50, v84
	v_add_u32_e32 v90, 0xc60, v84
	v_add_u32_e32 v91, 0xe70, v84
	v_add_u32_e32 v92, 0x1080, v84
	v_add_u32_e32 v93, 0x1290, v84
	v_add_u32_e32 v94, 0x14a0, v84
	v_add_u32_e32 v95, 0x16b0, v84
	v_add_u32_e32 v96, 0x18c0, v84
	v_add_u32_e32 v97, 0x1ad0, v84
	v_add_u32_e32 v98, 0x1ce0, v84
	v_add_u32_e32 v100, s2, v18
	v_cmp_lt_i32_e64 s[6:7], 0, v72
	v_lshl_add_u64 v[42:43], s[4:5], 0, v[0:1]
	v_add_u32_e32 v101, s3, v22
	v_add_u32_e32 v102, s2, v22
	v_add_u32_e32 v103, v2, v3
	v_add_u32_e32 v104, v2, v19
	v_add_u32_e32 v105, v23, v24
	v_add_u32_e32 v106, v8, v24
	v_add_u32_e32 v107, v7, v20
	s_mov_b32 s3, s90
	v_mov_b64_e32 v[70:71], v[38:39]
	v_mov_b64_e32 v[68:69], v[40:41]
	v_mov_b64_e32 v[66:67], v[44:45]
	v_mov_b64_e32 v[64:65], v[46:47]
	v_mov_b64_e32 v[62:63], v[48:49]
	v_mov_b64_e32 v[60:61], v[50:51]
	v_mov_b64_e32 v[58:59], v[52:53]
	v_mov_b64_e32 v[56:57], v[54:55]
	v_mov_b32_e32 v0, v126
	v_mov_b32_e32 v108, v33
	v_mov_b32_e32 v109, v32
	v_mov_b32_e32 v110, v31
	v_mov_b32_e32 v111, v30
	v_mov_b32_e32 v112, v28
	v_mov_b32_e32 v113, v26
	v_mov_b32_e32 v114, v17
	v_mov_b32_e32 v115, v16
	v_mov_b32_e32 v116, v15
	v_mov_b32_e32 v117, v14
	v_mov_b32_e32 v118, v12
	v_mov_b32_e32 v119, v11
	v_mov_b32_e32 v120, v9
	v_mov_b32_e32 v121, v5
	v_mov_b32_e32 v122, v4
	v_mov_b32_e32 v123, v6
	v_mov_b32_e32 v124, v10
	v_mov_b32_e32 v125, v13
	s_branch .LBB9_354
